# XCD barrier: early acquire invalidate + non-leader workgroups poll TOPGEN directly (no XGEN hop)
# speedup vs baseline: 1.0219x; 1.0044x over previous
; __device__ __forceinline__ unsigned xb_ld(unsigned* p)              { return __hip_atomic_load(p, __ATOMIC_RELAXED, __HIP_MEMORY_SCOPE_AGENT); }
; __device__ __forceinline__ unsigned xb_add(unsigned* p, unsigned v) { return __hip_atomic_fetch_add(p, v, __ATOMIC_RELAXED, __HIP_MEMORY_SCOPE_AGENT); }
; #define XB_SPIN(cond, bar) do { unsigned _sp = 0; while (cond) { __builtin_amdgcn_s_sleep(1); \
;     if ((++_sp & 255u) == 0u) { if (xb_ld(&(bar)[XB_TMO])) break; if (_sp > XB_SPIN_CAP) { atomicAdd(&(bar)[XB_TMO], 1u); break; } } } } while (0)
; __device__ __forceinline__ void xcd_barrier(const XcdBarrier& b) {
;     ...
;         unsigned nloc = b.st[0], nx = b.st[1];
;         if (nloc == 0u) { xcd_barrier_complete(bar, b.x, nloc, nx); b.st[0] = nloc; b.st[1] = nx; }
;         const unsigned old = xb_add(&bar[XB_XSUB(b.x)], 1u);
;         const unsigned gen = old / nloc;
;         if (old + 1u == (gen + 1u) * nloc) {
;             __builtin_amdgcn_fence(__ATOMIC_RELEASE, "agent");
;             asm volatile("s_waitcnt vmcnt(0)" ::: "memory");
;             const unsigned og = xb_add(&bar[XB_TOP], 1u);
;             const unsigned tg = og / nx;
;             if (og + 1u == (tg + 1u) * nx) xb_add(&bar[XB_TOPGEN], 1u);
;             else XB_SPIN(xb_ld(&bar[XB_TOPGEN]) == tg, bar);
;             __builtin_amdgcn_fence(__ATOMIC_ACQUIRE, "agent");
;             xb_add(&bar[XB_XGEN(b.x)], 1u);
;             asm volatile("s_waitcnt vmcnt(0)" ::: "memory");
;         } else {
;             XB_SPIN(xb_ld(&bar[XB_XGEN(b.x)]) == gen, bar);
.Lxs0_105:
	s_or_b64 exec, exec, s[6:7]
	v_cvt_f32_u32_e32 v4, v2
	s_waitcnt vmcnt(0)
	v_readfirstlane_b32 s4, v3
	v_sub_u32_e32 v3, 0, v2
	v_rcp_iflag_f32_e32 v4, v4
	v_add_u32_e32 v5, s4, v0
	v_mul_f32_e32 v4, 0x4f7ffffe, v4
	v_cvt_u32_f32_e32 v4, v4
	v_mul_lo_u32 v0, v3, v4
	v_mul_hi_u32 v0, v4, v0
	v_add_u32_e32 v0, v4, v0
	v_mul_hi_u32 v0, v5, v0
	v_mul_lo_u32 v3, v0, v2
	v_sub_u32_e32 v3, v5, v3
	v_add_u32_e32 v4, 1, v0
	v_cmp_ge_u32_e32 vcc, v3, v2
	s_nop 1
	v_cndmask_b32_e32 v0, v0, v4, vcc
	v_sub_u32_e32 v4, v3, v2
	v_cndmask_b32_e32 v3, v3, v4, vcc
	v_add_u32_e32 v4, 1, v0
	v_cmp_ge_u32_e32 vcc, v3, v2
	v_add_u32_e32 v3, 1, v5
	s_nop 0
	v_cndmask_b32_e32 v0, v0, v4, vcc
	v_mul_lo_u32 v4, v2, v0
	v_add_u32_e32 v2, v4, v2
	v_cmp_ne_u32_e32 vcc, v3, v2
	s_and_saveexec_b64 s[4:5], vcc
	s_xor_b64 s[4:5], exec, s[4:5]
	s_cbranch_execz .Lxs0_119
	s_waitcnt lgkmcnt(0)
	buffer_inv sc1
	v_readlane_b32 s10, v228, 15
	v_readlane_b32 s11, v228, 16
	v_mov_b32_e32 v1, 0
	s_nop 4
	s_add_u32 s10, s10, 0x3500
	s_addc_u32 s11, s11, 0
	global_load_dword v1, v1, s[10:11] sc1


; __device__ __forceinline__ unsigned xb_ld(unsigned* p)              { return __hip_atomic_load(p, __ATOMIC_RELAXED, __HIP_MEMORY_SCOPE_AGENT); }
; #define XB_SPIN(cond, bar) do { unsigned _sp = 0; while (cond) { __builtin_amdgcn_s_sleep(1); \
;     if ((++_sp & 255u) == 0u) { if (xb_ld(&(bar)[XB_TMO])) break; if (_sp > XB_SPIN_CAP) { atomicAdd(&(bar)[XB_TMO], 1u); break; } } } } while (0)
; __device__ __forceinline__ void xcd_barrier(const XcdBarrier& b) {
;     ...
;             XB_SPIN(xb_ld(&bar[XB_XGEN(b.x)]) == gen, bar);
	s_waitcnt vmcnt(0)
	v_cmp_eq_u32_e32 vcc, v1, v0
	s_and_saveexec_b64 s[6:7], vcc
	s_cbranch_execz .Lxs0_118
	v_readlane_b32 s12, v228, 2
	v_readlane_b32 s18, v228, 8
	v_readlane_b32 s13, v228, 3
	v_readlane_b32 s19, v228, 9
	s_add_u32 s8, s18, 0x179ed200
	v_readlane_b32 s14, v228, 4
	v_readlane_b32 s15, v228, 5
	s_addc_u32 s9, s19, 0
	s_mov_b32 s22, 1
	s_mov_b64 s[12:13], 0
	v_mov_b32_e32 v1, 0
	v_readlane_b32 s16, v228, 6
	v_readlane_b32 s17, v228, 7
	s_branch .Lxs0_109

; __device__ __forceinline__ unsigned xb_ld(unsigned* p)              { return __hip_atomic_load(p, __ATOMIC_RELAXED, __HIP_MEMORY_SCOPE_AGENT); }
; __device__ __forceinline__ unsigned xb_add(unsigned* p, unsigned v) { return __hip_atomic_fetch_add(p, v, __ATOMIC_RELAXED, __HIP_MEMORY_SCOPE_AGENT); }
; #define XB_SPIN(cond, bar) do { unsigned _sp = 0; while (cond) { __builtin_amdgcn_s_sleep(1); \
;     if ((++_sp & 255u) == 0u) { if (xb_ld(&(bar)[XB_TMO])) break; if (_sp > XB_SPIN_CAP) { atomicAdd(&(bar)[XB_TMO], 1u); break; } } } } while (0)
; __device__ __forceinline__ void xcd_barrier(const XcdBarrier& b) {
;     ...
;         unsigned nloc = b.st[0], nx = b.st[1];
;         if (nloc == 0u) { xcd_barrier_complete(bar, b.x, nloc, nx); b.st[0] = nloc; b.st[1] = nx; }
;         const unsigned old = xb_add(&bar[XB_XSUB(b.x)], 1u);
;         const unsigned gen = old / nloc;
;         if (old + 1u == (gen + 1u) * nloc) {
;             __builtin_amdgcn_fence(__ATOMIC_RELEASE, "agent");
;             asm volatile("s_waitcnt vmcnt(0)" ::: "memory");
;             const unsigned og = xb_add(&bar[XB_TOP], 1u);
;             const unsigned tg = og / nx;
;             if (og + 1u == (tg + 1u) * nx) xb_add(&bar[XB_TOPGEN], 1u);
;             else XB_SPIN(xb_ld(&bar[XB_TOPGEN]) == tg, bar);
;             __builtin_amdgcn_fence(__ATOMIC_ACQUIRE, "agent");
;             xb_add(&bar[XB_XGEN(b.x)], 1u);
;             asm volatile("s_waitcnt vmcnt(0)" ::: "memory");
;         } else {
;             XB_SPIN(xb_ld(&bar[XB_XGEN(b.x)]) == gen, bar);
.LBB0_942:
	s_or_b64 exec, exec, s[6:7]
	v_cvt_f32_u32_e32 v4, v2
	s_waitcnt vmcnt(0)
	v_readfirstlane_b32 s4, v3
	v_sub_u32_e32 v3, 0, v2
	v_rcp_iflag_f32_e32 v4, v4
	v_add_u32_e32 v5, s4, v1
	v_mul_f32_e32 v4, 0x4f7ffffe, v4
	v_cvt_u32_f32_e32 v4, v4
	v_mul_lo_u32 v1, v3, v4
	v_mul_hi_u32 v1, v4, v1
	v_add_u32_e32 v1, v4, v1
	v_mul_hi_u32 v1, v5, v1
	v_mul_lo_u32 v3, v1, v2
	v_sub_u32_e32 v3, v5, v3
	v_add_u32_e32 v4, 1, v1
	v_cmp_ge_u32_e32 vcc, v3, v2
	s_nop 1
	v_cndmask_b32_e32 v1, v1, v4, vcc
	v_sub_u32_e32 v4, v3, v2
	v_cndmask_b32_e32 v3, v3, v4, vcc
	v_add_u32_e32 v4, 1, v1
	v_cmp_ge_u32_e32 vcc, v3, v2
	v_add_u32_e32 v3, 1, v5
	s_nop 0
	v_cndmask_b32_e32 v1, v1, v4, vcc
	v_mul_lo_u32 v4, v2, v1
	v_add_u32_e32 v2, v4, v2
	v_cmp_ne_u32_e32 vcc, v3, v2
	s_and_saveexec_b64 s[4:5], vcc
	s_xor_b64 s[4:5], exec, s[4:5]
	s_cbranch_execz .LBB0_956
	s_waitcnt lgkmcnt(0)
	buffer_inv sc1
	v_readlane_b32 s10, v228, 15
	v_readlane_b32 s11, v228, 16
	v_mov_b32_e32 v0, 0
	s_nop 4
	s_add_u32 s10, s10, 0x3500
	s_addc_u32 s11, s11, 0
	global_load_dword v0, v0, s[10:11] sc1


; __device__ __forceinline__ unsigned xb_ld(unsigned* p)              { return __hip_atomic_load(p, __ATOMIC_RELAXED, __HIP_MEMORY_SCOPE_AGENT); }
; #define XB_SPIN(cond, bar) do { unsigned _sp = 0; while (cond) { __builtin_amdgcn_s_sleep(1); \
;     if ((++_sp & 255u) == 0u) { if (xb_ld(&(bar)[XB_TMO])) break; if (_sp > XB_SPIN_CAP) { atomicAdd(&(bar)[XB_TMO], 1u); break; } } } } while (0)
; __device__ __forceinline__ void xcd_barrier(const XcdBarrier& b) {
;     ...
;             XB_SPIN(xb_ld(&bar[XB_XGEN(b.x)]) == gen, bar);
	s_waitcnt vmcnt(0)
	v_cmp_eq_u32_e32 vcc, v0, v1
	s_and_saveexec_b64 s[6:7], vcc
	s_cbranch_execz .LBB0_955
	v_readlane_b32 s12, v228, 2
	v_readlane_b32 s18, v228, 8
	v_readlane_b32 s13, v228, 3
	v_readlane_b32 s19, v228, 9
	s_add_u32 s8, s18, 0x179ed200
	v_readlane_b32 s14, v228, 4
	v_readlane_b32 s15, v228, 5
	s_addc_u32 s9, s19, 0
	s_mov_b32 s22, 1
	s_mov_b64 s[12:13], 0
	v_mov_b32_e32 v0, 0
	v_readlane_b32 s16, v228, 6
	v_readlane_b32 s17, v228, 7
	s_branch .LBB0_946

; __device__ __forceinline__ unsigned xb_ld(unsigned* p)              { return __hip_atomic_load(p, __ATOMIC_RELAXED, __HIP_MEMORY_SCOPE_AGENT); }
; __device__ __forceinline__ unsigned xb_add(unsigned* p, unsigned v) { return __hip_atomic_fetch_add(p, v, __ATOMIC_RELAXED, __HIP_MEMORY_SCOPE_AGENT); }
; #define XB_SPIN(cond, bar) do { unsigned _sp = 0; while (cond) { __builtin_amdgcn_s_sleep(1); \
;     if ((++_sp & 255u) == 0u) { if (xb_ld(&(bar)[XB_TMO])) break; if (_sp > XB_SPIN_CAP) { atomicAdd(&(bar)[XB_TMO], 1u); break; } } } } while (0)
; __device__ __forceinline__ void xcd_barrier(const XcdBarrier& b) {
;     ...
;         unsigned nloc = b.st[0], nx = b.st[1];
;         if (nloc == 0u) { xcd_barrier_complete(bar, b.x, nloc, nx); b.st[0] = nloc; b.st[1] = nx; }
;         const unsigned old = xb_add(&bar[XB_XSUB(b.x)], 1u);
;         const unsigned gen = old / nloc;
;         if (old + 1u == (gen + 1u) * nloc) {
;             __builtin_amdgcn_fence(__ATOMIC_RELEASE, "agent");
;             asm volatile("s_waitcnt vmcnt(0)" ::: "memory");
;             const unsigned og = xb_add(&bar[XB_TOP], 1u);
;             const unsigned tg = og / nx;
;             if (og + 1u == (tg + 1u) * nx) xb_add(&bar[XB_TOPGEN], 1u);
;             else XB_SPIN(xb_ld(&bar[XB_TOPGEN]) == tg, bar);
;             __builtin_amdgcn_fence(__ATOMIC_ACQUIRE, "agent");
;             xb_add(&bar[XB_XGEN(b.x)], 1u);
;             asm volatile("s_waitcnt vmcnt(0)" ::: "memory");
;         } else {
;             XB_SPIN(xb_ld(&bar[XB_XGEN(b.x)]) == gen, bar);
.LBB0_1194:
	s_or_b64 exec, exec, s[6:7]
	v_cvt_f32_u32_e32 v4, v2
	s_waitcnt vmcnt(0)
	v_readfirstlane_b32 s4, v3
	v_sub_u32_e32 v3, 0, v2
	v_rcp_iflag_f32_e32 v4, v4
	v_add_u32_e32 v5, s4, v0
	v_mul_f32_e32 v4, 0x4f7ffffe, v4
	v_cvt_u32_f32_e32 v4, v4
	v_mul_lo_u32 v0, v3, v4
	v_mul_hi_u32 v0, v4, v0
	v_add_u32_e32 v0, v4, v0
	v_mul_hi_u32 v0, v5, v0
	v_mul_lo_u32 v3, v0, v2
	v_sub_u32_e32 v3, v5, v3
	v_add_u32_e32 v4, 1, v0
	v_cmp_ge_u32_e32 vcc, v3, v2
	s_nop 1
	v_cndmask_b32_e32 v0, v0, v4, vcc
	v_sub_u32_e32 v4, v3, v2
	v_cndmask_b32_e32 v3, v3, v4, vcc
	v_add_u32_e32 v4, 1, v0
	v_cmp_ge_u32_e32 vcc, v3, v2
	v_add_u32_e32 v3, 1, v5
	s_nop 0
	v_cndmask_b32_e32 v0, v0, v4, vcc
	v_mul_lo_u32 v4, v2, v0
	v_add_u32_e32 v2, v4, v2
	v_cmp_ne_u32_e32 vcc, v3, v2
	s_and_saveexec_b64 s[4:5], vcc
	s_xor_b64 s[4:5], exec, s[4:5]
	s_cbranch_execz .LBB0_1208
	s_waitcnt lgkmcnt(0)
	buffer_inv sc1
	v_readlane_b32 s10, v228, 15
	v_readlane_b32 s11, v228, 16
	v_mov_b32_e32 v1, 0
	s_nop 4
	s_add_u32 s10, s10, 0x3500
	s_addc_u32 s11, s11, 0
	global_load_dword v1, v1, s[10:11] sc1


; __device__ __forceinline__ unsigned xb_ld(unsigned* p)              { return __hip_atomic_load(p, __ATOMIC_RELAXED, __HIP_MEMORY_SCOPE_AGENT); }
; #define XB_SPIN(cond, bar) do { unsigned _sp = 0; while (cond) { __builtin_amdgcn_s_sleep(1); \
;     if ((++_sp & 255u) == 0u) { if (xb_ld(&(bar)[XB_TMO])) break; if (_sp > XB_SPIN_CAP) { atomicAdd(&(bar)[XB_TMO], 1u); break; } } } } while (0)
; __device__ __forceinline__ void xcd_barrier(const XcdBarrier& b) {
;     ...
;             XB_SPIN(xb_ld(&bar[XB_XGEN(b.x)]) == gen, bar);
	s_waitcnt vmcnt(0)
	v_cmp_eq_u32_e32 vcc, v1, v0
	s_and_saveexec_b64 s[6:7], vcc
	s_cbranch_execz .LBB0_1207
	v_readlane_b32 s12, v228, 2
	v_readlane_b32 s14, v228, 4
	v_readlane_b32 s15, v228, 5
	v_readlane_b32 s18, v228, 8
	v_readlane_b32 s19, v228, 9
	s_mov_b64 s[14:15], s[18:19]
	v_readlane_b32 s13, v228, 3
	s_add_u32 s8, s14, 0x179ed200
	s_addc_u32 s9, s15, 0
	s_mov_b32 s22, 1
	s_mov_b64 s[12:13], 0
	v_mov_b32_e32 v1, 0
	v_readlane_b32 s16, v228, 6
	v_readlane_b32 s17, v228, 7
	s_branch .LBB0_1198
